# merge-GEMM gate epilogue: pipelined gate loads (was one load round trip per block) + in-proj packed epilogue
# speedup vs baseline: 1.0095x; 1.0095x over previous
; #define GAS __attribute__((address_space(1)))
; __device__ __forceinline__ float bf_lo(unsigned u) { return __uint_as_float(u << 16); }
; __device__ __forceinline__ float bf_hi(unsigned u) { return __uint_as_float(u & 0xffff0000u); }
; __device__ __forceinline__ float frcp(float x) { return __builtin_amdgcn_rcpf(x); }
; __device__ __forceinline__ v4u pack8(const f32x4 a, const f32x4 b) { v4u w; w.x = cvt_pk_bf16(a[0], a[1]); w.y = cvt_pk_bf16(a[2], a[3]); w.z = cvt_pk_bf16(b[0], b[1]); w.w = cvt_pk_bf16(b[2], b[3]); return w; }
;     __device__ __forceinline__ void operator()(Acc& acc, const Unit& u, int wr, int wc, int fr, int fq, LAS unsigned char* lds) const {
;         const int row0 = u.pm * BM + wr * 64 + fr, c0 = u.pn * BM + wc * 32 + 8 * fq;
;         const GAS bf16* G0 = (const GAS bf16*)(ws + WS_GATE) + (size_t)u.seg * MTOT * 1024; const GAS bf16* G1 = G0 + (size_t)MTOT * 1024; GAS bf16* dst = (GAS bf16*)(ws + WS_MERGED);
;         const bool fin = u.seg == 2;
; #pragma unroll
;         for (int ai = 0; ai < 2; ++ai)
; #pragma unroll
;         for (int mh = 0; mh < 2; ++mh) {
;             v4u ga[2][2], gb[2][2];
; #pragma unroll
;             for (int mm = 0; mm < 2; ++mm)
; #pragma unroll
;                 for (int bj = 0; bj < 2; ++bj) { const size_t ro = (size_t)(row0 + ai * 128 + (2 * mh + mm) * 16) * 1024 + c0 + bj * 128; ga[mm][bj] = *(const GAS v4u*)(G0 + ro); gb[mm][bj] = fin ? ga[mm][bj] : *(const GAS v4u*)(G1 + ro); }
; #pragma unroll
;             for (int mm = 0; mm < 2; ++mm)
; #pragma unroll
;                 for (int bj = 0; bj < 2; ++bj) { const int m = 2 * mh + mm; const v4u x = ga[mm][bj], y = gb[mm][bj];
;                     f32x4 fa0 = {bf_lo(x.x), bf_hi(x.x), bf_lo(x.y), bf_hi(x.y)}, fa1 = {bf_lo(x.z), bf_hi(x.z), bf_lo(x.w), bf_hi(x.w)};
;                     if (!fin) { const f32x4 fb0 = {bf_lo(y.x), bf_hi(y.x), bf_lo(y.y), bf_hi(y.y)}, fb1 = {bf_lo(y.z), bf_hi(y.z), bf_lo(y.w), bf_hi(y.w)};
; #pragma unroll
;                         for (int j = 0; j < 4; ++j) { fa0[j] *= frcp(fb0[j]); fa1[j] *= frcp(fb1[j]); } }
;                     acc[ai][bj][m][0] *= fa0; acc[ai][bj][m][1] *= fa1;
;                     if (fin) *(GAS v4u*)(dst + (size_t)(row0 + ai * 128 + m * 16) * 1024 + c0 + bj * 128) = pack8(acc[ai][bj][m][0], acc[ai][bj][m][1]); }
.LBB0_960:
	v_lshl_add_u32 v190, s60, 8, v194
	v_lshl_add_u32 v191, s52, 8, v196
	s_mul_i32 s17, s61, 0x2480000
	s_mul_hi_i32 s13, s61, 0x2480000
	s_add_u32 s52, s75, s17
	s_addc_u32 s53, s88, s13
	s_add_u32 s64, s52, 0x2480000
	s_addc_u32 s65, s53, 0
	v_lshlrev_b32_e32 v190, 11, v190
	s_cmp_eq_u32 s61, 2
	s_cselect_b64 s[66:67], -1, 0
	s_cmp_lg_u32 s61, 2
	s_cselect_b64 s[60:61], -1, 0
	s_mov_b64 s[62:63], s[66:67]
	v_lshl_add_u32 v182, v191, 1, v190
	v_add_u32_e32 v183, 0x8000, v182
	v_add_u32_e32 v184, 0x10000, v182
	v_add_u32_e32 v185, 0x18000, v182
	v_add_u32_e32 v186, 0x40000, v182
	v_add_u32_e32 v187, 0x48000, v182
	v_add_u32_e32 v188, 0x50000, v182
	v_add_u32_e32 v189, 0x58000, v182
	s_and_b64 vcc, exec, s[66:67]
	s_cbranch_vccnz .Lmg_fin
	global_load_dwordx4 v[128:131], v182, s[52:53]
	global_load_dwordx4 v[132:135], v182, s[64:65]
	global_load_dwordx4 v[136:139], v182, s[52:53] offset:256
	global_load_dwordx4 v[140:143], v182, s[64:65] offset:256
	global_load_dwordx4 v[144:147], v183, s[52:53]
	global_load_dwordx4 v[148:151], v183, s[64:65]
	global_load_dwordx4 v[152:155], v183, s[52:53] offset:256
	global_load_dwordx4 v[156:159], v183, s[64:65] offset:256
	global_load_dwordx4 v[218:221], v184, s[52:53]
	global_load_dwordx4 v[222:225], v184, s[64:65]
	global_load_dwordx4 v[226:229], v184, s[52:53] offset:256
	global_load_dwordx4 v[230:233], v184, s[64:65] offset:256
	global_load_dwordx4 v[198:201], v185, s[52:53]
	global_load_dwordx4 v[202:205], v185, s[64:65]
	s_waitcnt vmcnt(12)
	v_lshlrev_b32_e32 v244, 16, v132
	v_and_b32_e32 v245, 0xffff0000, v132
	v_lshlrev_b32_e32 v246, 16, v133
	v_and_b32_e32 v247, 0xffff0000, v133
	v_lshlrev_b32_e32 v248, 16, v134
	v_and_b32_e32 v249, 0xffff0000, v134
	v_lshlrev_b32_e32 v250, 16, v135
	v_and_b32_e32 v251, 0xffff0000, v135
	v_rcp_f32_e32 v244, v244
	v_rcp_f32_e32 v245, v245
	v_rcp_f32_e32 v246, v246
	v_rcp_f32_e32 v247, v247
	v_rcp_f32_e32 v248, v248
	v_rcp_f32_e32 v249, v249
	v_rcp_f32_e32 v250, v250
	v_rcp_f32_e32 v251, v251
	v_lshlrev_b32_e32 v206, 16, v128
	v_and_b32_e32 v207, 0xffff0000, v128
	v_lshlrev_b32_e32 v208, 16, v129
	v_and_b32_e32 v209, 0xffff0000, v129
	v_lshlrev_b32_e32 v190, 16, v130
	v_and_b32_e32 v191, 0xffff0000, v130
	v_lshlrev_b32_e32 v192, 16, v131
	v_and_b32_e32 v193, 0xffff0000, v131
	global_load_dwordx4 v[128:131], v185, s[52:53] offset:256
	global_load_dwordx4 v[132:135], v185, s[64:65] offset:256
	v_pk_mul_f32 v[206:207], v[206:207], v[244:245]
	v_pk_mul_f32 v[208:209], v[208:209], v[246:247]
	v_pk_mul_f32 v[190:191], v[190:191], v[248:249]
	v_pk_mul_f32 v[192:193], v[192:193], v[250:251]
	v_pk_mul_f32 v[124:125], v[124:125], v[206:207]
	v_pk_mul_f32 v[126:127], v[126:127], v[208:209]
	v_pk_mul_f32 v[120:121], v[120:121], v[190:191]
	v_pk_mul_f32 v[122:123], v[122:123], v[192:193]
	s_waitcnt vmcnt(12)
	v_lshlrev_b32_e32 v244, 16, v140
	v_and_b32_e32 v245, 0xffff0000, v140
	v_lshlrev_b32_e32 v246, 16, v141
	v_and_b32_e32 v247, 0xffff0000, v141
	v_lshlrev_b32_e32 v248, 16, v142
	v_and_b32_e32 v249, 0xffff0000, v142
	v_lshlrev_b32_e32 v250, 16, v143
	v_and_b32_e32 v251, 0xffff0000, v143
	v_rcp_f32_e32 v244, v244
	v_rcp_f32_e32 v245, v245
	v_rcp_f32_e32 v246, v246
	v_rcp_f32_e32 v247, v247
	v_rcp_f32_e32 v248, v248
	v_rcp_f32_e32 v249, v249
	v_rcp_f32_e32 v250, v250
	v_rcp_f32_e32 v251, v251
	v_lshlrev_b32_e32 v206, 16, v136
	v_and_b32_e32 v207, 0xffff0000, v136
	v_lshlrev_b32_e32 v208, 16, v137
	v_and_b32_e32 v209, 0xffff0000, v137
	v_lshlrev_b32_e32 v190, 16, v138
	v_and_b32_e32 v191, 0xffff0000, v138
	v_lshlrev_b32_e32 v192, 16, v139
	v_and_b32_e32 v193, 0xffff0000, v139
	global_load_dwordx4 v[136:139], v186, s[52:53]
	global_load_dwordx4 v[140:143], v186, s[64:65]
	v_pk_mul_f32 v[206:207], v[206:207], v[244:245]
	v_pk_mul_f32 v[208:209], v[208:209], v[246:247]
	v_pk_mul_f32 v[190:191], v[190:191], v[248:249]
	v_pk_mul_f32 v[192:193], v[192:193], v[250:251]
	v_pk_mul_f32 v[92:93], v[92:93], v[206:207]
	v_pk_mul_f32 v[94:95], v[94:95], v[208:209]
	v_pk_mul_f32 v[88:89], v[88:89], v[190:191]
	v_pk_mul_f32 v[90:91], v[90:91], v[192:193]
	s_waitcnt vmcnt(12)
	v_lshlrev_b32_e32 v244, 16, v148
	v_and_b32_e32 v245, 0xffff0000, v148
	v_lshlrev_b32_e32 v246, 16, v149
	v_and_b32_e32 v247, 0xffff0000, v149
	v_lshlrev_b32_e32 v248, 16, v150
	v_and_b32_e32 v249, 0xffff0000, v150
	v_lshlrev_b32_e32 v250, 16, v151
	v_and_b32_e32 v251, 0xffff0000, v151
	v_rcp_f32_e32 v244, v244
	v_rcp_f32_e32 v245, v245
	v_rcp_f32_e32 v246, v246
	v_rcp_f32_e32 v247, v247
	v_rcp_f32_e32 v248, v248
	v_rcp_f32_e32 v249, v249
	v_rcp_f32_e32 v250, v250
	v_rcp_f32_e32 v251, v251
	v_lshlrev_b32_e32 v206, 16, v144
	v_and_b32_e32 v207, 0xffff0000, v144
	v_lshlrev_b32_e32 v208, 16, v145
	v_and_b32_e32 v209, 0xffff0000, v145
	v_lshlrev_b32_e32 v190, 16, v146
	v_and_b32_e32 v191, 0xffff0000, v146
	v_lshlrev_b32_e32 v192, 16, v147
	v_and_b32_e32 v193, 0xffff0000, v147
	global_load_dwordx4 v[144:147], v186, s[52:53] offset:256
	global_load_dwordx4 v[148:151], v186, s[64:65] offset:256
	v_pk_mul_f32 v[206:207], v[206:207], v[244:245]
	v_pk_mul_f32 v[208:209], v[208:209], v[246:247]
	v_pk_mul_f32 v[190:191], v[190:191], v[248:249]
	v_pk_mul_f32 v[192:193], v[192:193], v[250:251]
	v_pk_mul_f32 v[116:117], v[116:117], v[206:207]
	v_pk_mul_f32 v[118:119], v[118:119], v[208:209]
	v_pk_mul_f32 v[112:113], v[112:113], v[190:191]
	v_pk_mul_f32 v[114:115], v[114:115], v[192:193]
	s_waitcnt vmcnt(12)
; #define GAS __attribute__((address_space(1)))
; __device__ __forceinline__ float bf_lo(unsigned u) { return __uint_as_float(u << 16); }
; __device__ __forceinline__ float bf_hi(unsigned u) { return __uint_as_float(u & 0xffff0000u); }
; __device__ __forceinline__ float frcp(float x) { return __builtin_amdgcn_rcpf(x); }
;     __device__ __forceinline__ void operator()(Acc& acc, const Unit& u, int wr, int wc, int fr, int fq, LAS unsigned char* lds) const {
;     ...
;                 for (int bj = 0; bj < 2; ++bj) { const size_t ro = (size_t)(row0 + ai * 128 + (2 * mh + mm) * 16) * 1024 + c0 + bj * 128; ga[mm][bj] = *(const GAS v4u*)(G0 + ro); gb[mm][bj] = fin ? ga[mm][bj] : *(const GAS v4u*)(G1 + ro); }
; #pragma unroll
;             for (int mm = 0; mm < 2; ++mm)
; #pragma unroll
;                 for (int bj = 0; bj < 2; ++bj) { const int m = 2 * mh + mm; const v4u x = ga[mm][bj], y = gb[mm][bj];
;                     f32x4 fa0 = {bf_lo(x.x), bf_hi(x.x), bf_lo(x.y), bf_hi(x.y)}, fa1 = {bf_lo(x.z), bf_hi(x.z), bf_lo(x.w), bf_hi(x.w)};
;                     if (!fin) { const f32x4 fb0 = {bf_lo(y.x), bf_hi(y.x), bf_lo(y.y), bf_hi(y.y)}, fb1 = {bf_lo(y.z), bf_hi(y.z), bf_lo(y.w), bf_hi(y.w)};
; #pragma unroll
;                         for (int j = 0; j < 4; ++j) { fa0[j] *= frcp(fb0[j]); fa1[j] *= frcp(fb1[j]); } }
;                     acc[ai][bj][m][0] *= fa0; acc[ai][bj][m][1] *= fa1;
	v_lshlrev_b32_e32 v244, 16, v156
	v_and_b32_e32 v245, 0xffff0000, v156
	v_lshlrev_b32_e32 v246, 16, v157
	v_and_b32_e32 v247, 0xffff0000, v157
	v_lshlrev_b32_e32 v248, 16, v158
	v_and_b32_e32 v249, 0xffff0000, v158
	v_lshlrev_b32_e32 v250, 16, v159
	v_and_b32_e32 v251, 0xffff0000, v159
	v_rcp_f32_e32 v244, v244
	v_rcp_f32_e32 v245, v245
	v_rcp_f32_e32 v246, v246
	v_rcp_f32_e32 v247, v247
	v_rcp_f32_e32 v248, v248
	v_rcp_f32_e32 v249, v249
	v_rcp_f32_e32 v250, v250
	v_rcp_f32_e32 v251, v251
	v_lshlrev_b32_e32 v206, 16, v152
	v_and_b32_e32 v207, 0xffff0000, v152
	v_lshlrev_b32_e32 v208, 16, v153
	v_and_b32_e32 v209, 0xffff0000, v153
	v_lshlrev_b32_e32 v190, 16, v154
	v_and_b32_e32 v191, 0xffff0000, v154
	v_lshlrev_b32_e32 v192, 16, v155
	v_and_b32_e32 v193, 0xffff0000, v155
	global_load_dwordx4 v[152:155], v187, s[52:53]
	global_load_dwordx4 v[156:159], v187, s[64:65]
	v_pk_mul_f32 v[206:207], v[206:207], v[244:245]
	v_pk_mul_f32 v[208:209], v[208:209], v[246:247]
	v_pk_mul_f32 v[190:191], v[190:191], v[248:249]
	v_pk_mul_f32 v[192:193], v[192:193], v[250:251]
	v_pk_mul_f32 v[84:85], v[84:85], v[206:207]
	v_pk_mul_f32 v[86:87], v[86:87], v[208:209]
	v_pk_mul_f32 v[80:81], v[80:81], v[190:191]
	v_pk_mul_f32 v[82:83], v[82:83], v[192:193]
	s_waitcnt vmcnt(12)
	v_lshlrev_b32_e32 v244, 16, v222
	v_and_b32_e32 v245, 0xffff0000, v222
	v_lshlrev_b32_e32 v246, 16, v223
	v_and_b32_e32 v247, 0xffff0000, v223
	v_lshlrev_b32_e32 v248, 16, v224
	v_and_b32_e32 v249, 0xffff0000, v224
	v_lshlrev_b32_e32 v250, 16, v225
	v_and_b32_e32 v251, 0xffff0000, v225
	v_rcp_f32_e32 v244, v244
	v_rcp_f32_e32 v245, v245
	v_rcp_f32_e32 v246, v246
	v_rcp_f32_e32 v247, v247
	v_rcp_f32_e32 v248, v248
	v_rcp_f32_e32 v249, v249
	v_rcp_f32_e32 v250, v250
	v_rcp_f32_e32 v251, v251
	v_lshlrev_b32_e32 v206, 16, v218
	v_and_b32_e32 v207, 0xffff0000, v218
	v_lshlrev_b32_e32 v208, 16, v219
	v_and_b32_e32 v209, 0xffff0000, v219
	v_lshlrev_b32_e32 v190, 16, v220
	v_and_b32_e32 v191, 0xffff0000, v220
	v_lshlrev_b32_e32 v192, 16, v221
	v_and_b32_e32 v193, 0xffff0000, v221
	global_load_dwordx4 v[218:221], v187, s[52:53] offset:256
	global_load_dwordx4 v[222:225], v187, s[64:65] offset:256
	v_pk_mul_f32 v[206:207], v[206:207], v[244:245]
	v_pk_mul_f32 v[208:209], v[208:209], v[246:247]
	v_pk_mul_f32 v[190:191], v[190:191], v[248:249]
	v_pk_mul_f32 v[192:193], v[192:193], v[250:251]
	v_pk_mul_f32 v[108:109], v[108:109], v[206:207]
	v_pk_mul_f32 v[110:111], v[110:111], v[208:209]
	v_pk_mul_f32 v[104:105], v[104:105], v[190:191]
	v_pk_mul_f32 v[106:107], v[106:107], v[192:193]
	s_waitcnt vmcnt(12)
	v_lshlrev_b32_e32 v244, 16, v230
	v_and_b32_e32 v245, 0xffff0000, v230
	v_lshlrev_b32_e32 v246, 16, v231
	v_and_b32_e32 v247, 0xffff0000, v231
	v_lshlrev_b32_e32 v248, 16, v232
	v_and_b32_e32 v249, 0xffff0000, v232
	v_lshlrev_b32_e32 v250, 16, v233
	v_and_b32_e32 v251, 0xffff0000, v233
	v_rcp_f32_e32 v244, v244
	v_rcp_f32_e32 v245, v245
	v_rcp_f32_e32 v246, v246
	v_rcp_f32_e32 v247, v247
	v_rcp_f32_e32 v248, v248
	v_rcp_f32_e32 v249, v249
	v_rcp_f32_e32 v250, v250
	v_rcp_f32_e32 v251, v251
	v_lshlrev_b32_e32 v206, 16, v226
	v_and_b32_e32 v207, 0xffff0000, v226
	v_lshlrev_b32_e32 v208, 16, v227
	v_and_b32_e32 v209, 0xffff0000, v227
	v_lshlrev_b32_e32 v190, 16, v228
	v_and_b32_e32 v191, 0xffff0000, v228
	v_lshlrev_b32_e32 v192, 16, v229
	v_and_b32_e32 v193, 0xffff0000, v229
	global_load_dwordx4 v[226:229], v188, s[52:53]
	global_load_dwordx4 v[230:233], v188, s[64:65]
	v_pk_mul_f32 v[206:207], v[206:207], v[244:245]
	v_pk_mul_f32 v[208:209], v[208:209], v[246:247]
	v_pk_mul_f32 v[190:191], v[190:191], v[248:249]
	v_pk_mul_f32 v[192:193], v[192:193], v[250:251]
	v_pk_mul_f32 v[76:77], v[76:77], v[206:207]
	v_pk_mul_f32 v[78:79], v[78:79], v[208:209]
	v_pk_mul_f32 v[72:73], v[72:73], v[190:191]
	v_pk_mul_f32 v[74:75], v[74:75], v[192:193]
	s_waitcnt vmcnt(12)
	v_lshlrev_b32_e32 v244, 16, v202
	v_and_b32_e32 v245, 0xffff0000, v202
	v_lshlrev_b32_e32 v246, 16, v203
	v_and_b32_e32 v247, 0xffff0000, v203
	v_lshlrev_b32_e32 v248, 16, v204
	v_and_b32_e32 v249, 0xffff0000, v204
	v_lshlrev_b32_e32 v250, 16, v205
	v_and_b32_e32 v251, 0xffff0000, v205
	v_rcp_f32_e32 v244, v244
	v_rcp_f32_e32 v245, v245
	v_rcp_f32_e32 v246, v246
	v_rcp_f32_e32 v247, v247
	v_rcp_f32_e32 v248, v248
	v_rcp_f32_e32 v249, v249
	v_rcp_f32_e32 v250, v250
	v_rcp_f32_e32 v251, v251
	v_lshlrev_b32_e32 v206, 16, v198
	v_and_b32_e32 v207, 0xffff0000, v198
	v_lshlrev_b32_e32 v208, 16, v199
	v_and_b32_e32 v209, 0xffff0000, v199
	v_lshlrev_b32_e32 v190, 16, v200
	v_and_b32_e32 v191, 0xffff0000, v200
	v_lshlrev_b32_e32 v192, 16, v201
	v_and_b32_e32 v193, 0xffff0000, v201
	global_load_dwordx4 v[198:201], v188, s[52:53] offset:256
	global_load_dwordx4 v[202:205], v188, s[64:65] offset:256
	v_pk_mul_f32 v[206:207], v[206:207], v[244:245]
	v_pk_mul_f32 v[208:209], v[208:209], v[246:247]
	v_pk_mul_f32 v[190:191], v[190:191], v[248:249]
	v_pk_mul_f32 v[192:193], v[192:193], v[250:251]
	v_pk_mul_f32 v[100:101], v[100:101], v[206:207]
	v_pk_mul_f32 v[102:103], v[102:103], v[208:209]
	v_pk_mul_f32 v[96:97], v[96:97], v[190:191]
	v_pk_mul_f32 v[98:99], v[98:99], v[192:193]
	s_waitcnt vmcnt(12)
; #define GAS __attribute__((address_space(1)))
; __device__ __forceinline__ float bf_lo(unsigned u) { return __uint_as_float(u << 16); }
; __device__ __forceinline__ float bf_hi(unsigned u) { return __uint_as_float(u & 0xffff0000u); }
; __device__ __forceinline__ float frcp(float x) { return __builtin_amdgcn_rcpf(x); }
;     __device__ __forceinline__ void operator()(Acc& acc, const Unit& u, int wr, int wc, int fr, int fq, LAS unsigned char* lds) const {
;     ...
;                 for (int bj = 0; bj < 2; ++bj) { const size_t ro = (size_t)(row0 + ai * 128 + (2 * mh + mm) * 16) * 1024 + c0 + bj * 128; ga[mm][bj] = *(const GAS v4u*)(G0 + ro); gb[mm][bj] = fin ? ga[mm][bj] : *(const GAS v4u*)(G1 + ro); }
; #pragma unroll
;             for (int mm = 0; mm < 2; ++mm)
; #pragma unroll
;                 for (int bj = 0; bj < 2; ++bj) { const int m = 2 * mh + mm; const v4u x = ga[mm][bj], y = gb[mm][bj];
;                     f32x4 fa0 = {bf_lo(x.x), bf_hi(x.x), bf_lo(x.y), bf_hi(x.y)}, fa1 = {bf_lo(x.z), bf_hi(x.z), bf_lo(x.w), bf_hi(x.w)};
;                     if (!fin) { const f32x4 fb0 = {bf_lo(y.x), bf_hi(y.x), bf_lo(y.y), bf_hi(y.y)}, fb1 = {bf_lo(y.z), bf_hi(y.z), bf_lo(y.w), bf_hi(y.w)};
; #pragma unroll
;                         for (int j = 0; j < 4; ++j) { fa0[j] *= frcp(fb0[j]); fa1[j] *= frcp(fb1[j]); } }
;                     acc[ai][bj][m][0] *= fa0; acc[ai][bj][m][1] *= fa1;
	v_lshlrev_b32_e32 v244, 16, v132
	v_and_b32_e32 v245, 0xffff0000, v132
	v_lshlrev_b32_e32 v246, 16, v133
	v_and_b32_e32 v247, 0xffff0000, v133
	v_lshlrev_b32_e32 v248, 16, v134
	v_and_b32_e32 v249, 0xffff0000, v134
	v_lshlrev_b32_e32 v250, 16, v135
	v_and_b32_e32 v251, 0xffff0000, v135
	v_rcp_f32_e32 v244, v244
	v_rcp_f32_e32 v245, v245
	v_rcp_f32_e32 v246, v246
	v_rcp_f32_e32 v247, v247
	v_rcp_f32_e32 v248, v248
	v_rcp_f32_e32 v249, v249
	v_rcp_f32_e32 v250, v250
	v_rcp_f32_e32 v251, v251
	v_lshlrev_b32_e32 v206, 16, v128
	v_and_b32_e32 v207, 0xffff0000, v128
	v_lshlrev_b32_e32 v208, 16, v129
	v_and_b32_e32 v209, 0xffff0000, v129
	v_lshlrev_b32_e32 v190, 16, v130
	v_and_b32_e32 v191, 0xffff0000, v130
	v_lshlrev_b32_e32 v192, 16, v131
	v_and_b32_e32 v193, 0xffff0000, v131
	global_load_dwordx4 v[128:131], v189, s[52:53]
	global_load_dwordx4 v[132:135], v189, s[64:65]
	v_pk_mul_f32 v[206:207], v[206:207], v[244:245]
	v_pk_mul_f32 v[208:209], v[208:209], v[246:247]
	v_pk_mul_f32 v[190:191], v[190:191], v[248:249]
	v_pk_mul_f32 v[192:193], v[192:193], v[250:251]
	v_pk_mul_f32 v[68:69], v[68:69], v[206:207]
	v_pk_mul_f32 v[70:71], v[70:71], v[208:209]
	v_pk_mul_f32 v[64:65], v[64:65], v[190:191]
	v_pk_mul_f32 v[66:67], v[66:67], v[192:193]
	s_waitcnt vmcnt(12)
	v_lshlrev_b32_e32 v244, 16, v140
	v_and_b32_e32 v245, 0xffff0000, v140
	v_lshlrev_b32_e32 v246, 16, v141
	v_and_b32_e32 v247, 0xffff0000, v141
	v_lshlrev_b32_e32 v248, 16, v142
	v_and_b32_e32 v249, 0xffff0000, v142
	v_lshlrev_b32_e32 v250, 16, v143
	v_and_b32_e32 v251, 0xffff0000, v143
	v_rcp_f32_e32 v244, v244
	v_rcp_f32_e32 v245, v245
	v_rcp_f32_e32 v246, v246
	v_rcp_f32_e32 v247, v247
	v_rcp_f32_e32 v248, v248
	v_rcp_f32_e32 v249, v249
	v_rcp_f32_e32 v250, v250
	v_rcp_f32_e32 v251, v251
	v_lshlrev_b32_e32 v206, 16, v136
	v_and_b32_e32 v207, 0xffff0000, v136
	v_lshlrev_b32_e32 v208, 16, v137
	v_and_b32_e32 v209, 0xffff0000, v137
	v_lshlrev_b32_e32 v190, 16, v138
	v_and_b32_e32 v191, 0xffff0000, v138
	v_lshlrev_b32_e32 v192, 16, v139
	v_and_b32_e32 v193, 0xffff0000, v139
	global_load_dwordx4 v[136:139], v189, s[52:53] offset:256
	global_load_dwordx4 v[140:143], v189, s[64:65] offset:256
	v_pk_mul_f32 v[206:207], v[206:207], v[244:245]
	v_pk_mul_f32 v[208:209], v[208:209], v[246:247]
	v_pk_mul_f32 v[190:191], v[190:191], v[248:249]
	v_pk_mul_f32 v[192:193], v[192:193], v[250:251]
	v_pk_mul_f32 v[60:61], v[60:61], v[206:207]
	v_pk_mul_f32 v[62:63], v[62:63], v[208:209]
	v_pk_mul_f32 v[56:57], v[56:57], v[190:191]
	v_pk_mul_f32 v[58:59], v[58:59], v[192:193]
	s_waitcnt vmcnt(12)
	v_lshlrev_b32_e32 v244, 16, v148
	v_and_b32_e32 v245, 0xffff0000, v148
	v_lshlrev_b32_e32 v246, 16, v149
	v_and_b32_e32 v247, 0xffff0000, v149
	v_lshlrev_b32_e32 v248, 16, v150
	v_and_b32_e32 v249, 0xffff0000, v150
	v_lshlrev_b32_e32 v250, 16, v151
	v_and_b32_e32 v251, 0xffff0000, v151
	v_rcp_f32_e32 v244, v244
	v_rcp_f32_e32 v245, v245
	v_rcp_f32_e32 v246, v246
	v_rcp_f32_e32 v247, v247
	v_rcp_f32_e32 v248, v248
	v_rcp_f32_e32 v249, v249
	v_rcp_f32_e32 v250, v250
	v_rcp_f32_e32 v251, v251
	v_lshlrev_b32_e32 v206, 16, v144
	v_and_b32_e32 v207, 0xffff0000, v144
	v_lshlrev_b32_e32 v208, 16, v145
	v_and_b32_e32 v209, 0xffff0000, v145
	v_lshlrev_b32_e32 v190, 16, v146
	v_and_b32_e32 v191, 0xffff0000, v146
	v_lshlrev_b32_e32 v192, 16, v147
	v_and_b32_e32 v193, 0xffff0000, v147
	v_pk_mul_f32 v[206:207], v[206:207], v[244:245]
	v_pk_mul_f32 v[208:209], v[208:209], v[246:247]
	v_pk_mul_f32 v[190:191], v[190:191], v[248:249]
	v_pk_mul_f32 v[192:193], v[192:193], v[250:251]
	v_pk_mul_f32 v[28:29], v[28:29], v[206:207]
	v_pk_mul_f32 v[30:31], v[30:31], v[208:209]
	v_pk_mul_f32 v[24:25], v[24:25], v[190:191]
	v_pk_mul_f32 v[26:27], v[26:27], v[192:193]
	s_waitcnt vmcnt(10)
	v_lshlrev_b32_e32 v244, 16, v156
	v_and_b32_e32 v245, 0xffff0000, v156
	v_lshlrev_b32_e32 v246, 16, v157
	v_and_b32_e32 v247, 0xffff0000, v157
	v_lshlrev_b32_e32 v248, 16, v158
	v_and_b32_e32 v249, 0xffff0000, v158
	v_lshlrev_b32_e32 v250, 16, v159
	v_and_b32_e32 v251, 0xffff0000, v159
	v_rcp_f32_e32 v244, v244
	v_rcp_f32_e32 v245, v245
	v_rcp_f32_e32 v246, v246
	v_rcp_f32_e32 v247, v247
	v_rcp_f32_e32 v248, v248
	v_rcp_f32_e32 v249, v249
	v_rcp_f32_e32 v250, v250
	v_rcp_f32_e32 v251, v251
	v_lshlrev_b32_e32 v206, 16, v152
	v_and_b32_e32 v207, 0xffff0000, v152
	v_lshlrev_b32_e32 v208, 16, v153
	v_and_b32_e32 v209, 0xffff0000, v153
	v_lshlrev_b32_e32 v190, 16, v154
	v_and_b32_e32 v191, 0xffff0000, v154
	v_lshlrev_b32_e32 v192, 16, v155
	v_and_b32_e32 v193, 0xffff0000, v155
	v_pk_mul_f32 v[206:207], v[206:207], v[244:245]
	v_pk_mul_f32 v[208:209], v[208:209], v[246:247]
	v_pk_mul_f32 v[190:191], v[190:191], v[248:249]
	v_pk_mul_f32 v[192:193], v[192:193], v[250:251]
	v_pk_mul_f32 v[52:53], v[52:53], v[206:207]
	v_pk_mul_f32 v[54:55], v[54:55], v[208:209]
	v_pk_mul_f32 v[48:49], v[48:49], v[190:191]
	v_pk_mul_f32 v[50:51], v[50:51], v[192:193]
	s_waitcnt vmcnt(8)
	v_lshlrev_b32_e32 v244, 16, v222
	v_and_b32_e32 v245, 0xffff0000, v222
	v_lshlrev_b32_e32 v246, 16, v223
	v_and_b32_e32 v247, 0xffff0000, v223
	v_lshlrev_b32_e32 v248, 16, v224
	v_and_b32_e32 v249, 0xffff0000, v224
	v_lshlrev_b32_e32 v250, 16, v225
	v_and_b32_e32 v251, 0xffff0000, v225
	v_rcp_f32_e32 v244, v244
	v_rcp_f32_e32 v245, v245
	v_rcp_f32_e32 v246, v246
	v_rcp_f32_e32 v247, v247
	v_rcp_f32_e32 v248, v248
	v_rcp_f32_e32 v249, v249
	v_rcp_f32_e32 v250, v250
	v_rcp_f32_e32 v251, v251
	v_lshlrev_b32_e32 v206, 16, v218
	v_and_b32_e32 v207, 0xffff0000, v218
	v_lshlrev_b32_e32 v208, 16, v219
	v_and_b32_e32 v209, 0xffff0000, v219
	v_lshlrev_b32_e32 v190, 16, v220
	v_and_b32_e32 v191, 0xffff0000, v220
	v_lshlrev_b32_e32 v192, 16, v221
	v_and_b32_e32 v193, 0xffff0000, v221
	v_pk_mul_f32 v[206:207], v[206:207], v[244:245]
	v_pk_mul_f32 v[208:209], v[208:209], v[246:247]
	v_pk_mul_f32 v[190:191], v[190:191], v[248:249]
	v_pk_mul_f32 v[192:193], v[192:193], v[250:251]
	v_pk_mul_f32 v[20:21], v[20:21], v[206:207]
	v_pk_mul_f32 v[22:23], v[22:23], v[208:209]
	v_pk_mul_f32 v[16:17], v[16:17], v[190:191]
	v_pk_mul_f32 v[18:19], v[18:19], v[192:193]
	s_waitcnt vmcnt(6)
; #define GAS __attribute__((address_space(1)))
; __device__ __forceinline__ float bf_lo(unsigned u) { return __uint_as_float(u << 16); }
; __device__ __forceinline__ float bf_hi(unsigned u) { return __uint_as_float(u & 0xffff0000u); }
; __device__ __forceinline__ float frcp(float x) { return __builtin_amdgcn_rcpf(x); }
;     __device__ __forceinline__ void operator()(Acc& acc, const Unit& u, int wr, int wc, int fr, int fq, LAS unsigned char* lds) const {
;     ...
;                 for (int bj = 0; bj < 2; ++bj) { const size_t ro = (size_t)(row0 + ai * 128 + (2 * mh + mm) * 16) * 1024 + c0 + bj * 128; ga[mm][bj] = *(const GAS v4u*)(G0 + ro); gb[mm][bj] = fin ? ga[mm][bj] : *(const GAS v4u*)(G1 + ro); }
; #pragma unroll
;             for (int mm = 0; mm < 2; ++mm)
; #pragma unroll
;                 for (int bj = 0; bj < 2; ++bj) { const int m = 2 * mh + mm; const v4u x = ga[mm][bj], y = gb[mm][bj];
;                     f32x4 fa0 = {bf_lo(x.x), bf_hi(x.x), bf_lo(x.y), bf_hi(x.y)}, fa1 = {bf_lo(x.z), bf_hi(x.z), bf_lo(x.w), bf_hi(x.w)};
;                     if (!fin) { const f32x4 fb0 = {bf_lo(y.x), bf_hi(y.x), bf_lo(y.y), bf_hi(y.y)}, fb1 = {bf_lo(y.z), bf_hi(y.z), bf_lo(y.w), bf_hi(y.w)};
; #pragma unroll
;                         for (int j = 0; j < 4; ++j) { fa0[j] *= frcp(fb0[j]); fa1[j] *= frcp(fb1[j]); } }
;                     acc[ai][bj][m][0] *= fa0; acc[ai][bj][m][1] *= fa1;
	v_lshlrev_b32_e32 v244, 16, v230
	v_and_b32_e32 v245, 0xffff0000, v230
	v_lshlrev_b32_e32 v246, 16, v231
	v_and_b32_e32 v247, 0xffff0000, v231
	v_lshlrev_b32_e32 v248, 16, v232
	v_and_b32_e32 v249, 0xffff0000, v232
	v_lshlrev_b32_e32 v250, 16, v233
	v_and_b32_e32 v251, 0xffff0000, v233
	v_rcp_f32_e32 v244, v244
	v_rcp_f32_e32 v245, v245
	v_rcp_f32_e32 v246, v246
	v_rcp_f32_e32 v247, v247
	v_rcp_f32_e32 v248, v248
	v_rcp_f32_e32 v249, v249
	v_rcp_f32_e32 v250, v250
	v_rcp_f32_e32 v251, v251
	v_lshlrev_b32_e32 v206, 16, v226
	v_and_b32_e32 v207, 0xffff0000, v226
	v_lshlrev_b32_e32 v208, 16, v227
	v_and_b32_e32 v209, 0xffff0000, v227
	v_lshlrev_b32_e32 v190, 16, v228
	v_and_b32_e32 v191, 0xffff0000, v228
	v_lshlrev_b32_e32 v192, 16, v229
	v_and_b32_e32 v193, 0xffff0000, v229
	v_pk_mul_f32 v[206:207], v[206:207], v[244:245]
	v_pk_mul_f32 v[208:209], v[208:209], v[246:247]
	v_pk_mul_f32 v[190:191], v[190:191], v[248:249]
	v_pk_mul_f32 v[192:193], v[192:193], v[250:251]
	v_pk_mul_f32 v[44:45], v[44:45], v[206:207]
	v_pk_mul_f32 v[46:47], v[46:47], v[208:209]
	v_pk_mul_f32 v[40:41], v[40:41], v[190:191]
	v_pk_mul_f32 v[42:43], v[42:43], v[192:193]
	s_waitcnt vmcnt(4)
	v_lshlrev_b32_e32 v244, 16, v202
	v_and_b32_e32 v245, 0xffff0000, v202
	v_lshlrev_b32_e32 v246, 16, v203
	v_and_b32_e32 v247, 0xffff0000, v203
	v_lshlrev_b32_e32 v248, 16, v204
	v_and_b32_e32 v249, 0xffff0000, v204
	v_lshlrev_b32_e32 v250, 16, v205
	v_and_b32_e32 v251, 0xffff0000, v205
	v_rcp_f32_e32 v244, v244
	v_rcp_f32_e32 v245, v245
	v_rcp_f32_e32 v246, v246
	v_rcp_f32_e32 v247, v247
	v_rcp_f32_e32 v248, v248
	v_rcp_f32_e32 v249, v249
	v_rcp_f32_e32 v250, v250
	v_rcp_f32_e32 v251, v251
	v_lshlrev_b32_e32 v206, 16, v198
	v_and_b32_e32 v207, 0xffff0000, v198
	v_lshlrev_b32_e32 v208, 16, v199
	v_and_b32_e32 v209, 0xffff0000, v199
	v_lshlrev_b32_e32 v190, 16, v200
	v_and_b32_e32 v191, 0xffff0000, v200
	v_lshlrev_b32_e32 v192, 16, v201
	v_and_b32_e32 v193, 0xffff0000, v201
	v_pk_mul_f32 v[206:207], v[206:207], v[244:245]
	v_pk_mul_f32 v[208:209], v[208:209], v[246:247]
	v_pk_mul_f32 v[190:191], v[190:191], v[248:249]
	v_pk_mul_f32 v[192:193], v[192:193], v[250:251]
	v_pk_mul_f32 v[12:13], v[12:13], v[206:207]
	v_pk_mul_f32 v[14:15], v[14:15], v[208:209]
	v_pk_mul_f32 v[8:9], v[8:9], v[190:191]
	v_pk_mul_f32 v[10:11], v[10:11], v[192:193]
	s_waitcnt vmcnt(2)
	v_lshlrev_b32_e32 v244, 16, v132
	v_and_b32_e32 v245, 0xffff0000, v132
	v_lshlrev_b32_e32 v246, 16, v133
	v_and_b32_e32 v247, 0xffff0000, v133
	v_lshlrev_b32_e32 v248, 16, v134
	v_and_b32_e32 v249, 0xffff0000, v134
	v_lshlrev_b32_e32 v250, 16, v135
	v_and_b32_e32 v251, 0xffff0000, v135
	v_rcp_f32_e32 v244, v244
	v_rcp_f32_e32 v245, v245
	v_rcp_f32_e32 v246, v246
	v_rcp_f32_e32 v247, v247
	v_rcp_f32_e32 v248, v248
	v_rcp_f32_e32 v249, v249
	v_rcp_f32_e32 v250, v250
	v_rcp_f32_e32 v251, v251
	v_lshlrev_b32_e32 v206, 16, v128
	v_and_b32_e32 v207, 0xffff0000, v128
	v_lshlrev_b32_e32 v208, 16, v129
	v_and_b32_e32 v209, 0xffff0000, v129
	v_lshlrev_b32_e32 v190, 16, v130
	v_and_b32_e32 v191, 0xffff0000, v130
	v_lshlrev_b32_e32 v192, 16, v131
	v_and_b32_e32 v193, 0xffff0000, v131
	v_pk_mul_f32 v[206:207], v[206:207], v[244:245]
	v_pk_mul_f32 v[208:209], v[208:209], v[246:247]
	v_pk_mul_f32 v[190:191], v[190:191], v[248:249]
	v_pk_mul_f32 v[192:193], v[192:193], v[250:251]
	v_pk_mul_f32 v[36:37], v[36:37], v[206:207]
	v_pk_mul_f32 v[38:39], v[38:39], v[208:209]
	v_pk_mul_f32 v[32:33], v[32:33], v[190:191]
	v_pk_mul_f32 v[34:35], v[34:35], v[192:193]
	s_waitcnt vmcnt(0)
	v_lshlrev_b32_e32 v244, 16, v140
	v_and_b32_e32 v245, 0xffff0000, v140
	v_lshlrev_b32_e32 v246, 16, v141
	v_and_b32_e32 v247, 0xffff0000, v141
	v_lshlrev_b32_e32 v248, 16, v142
	v_and_b32_e32 v249, 0xffff0000, v142
	v_lshlrev_b32_e32 v250, 16, v143
	v_and_b32_e32 v251, 0xffff0000, v143
	v_rcp_f32_e32 v244, v244
	v_rcp_f32_e32 v245, v245
	v_rcp_f32_e32 v246, v246
	v_rcp_f32_e32 v247, v247
	v_rcp_f32_e32 v248, v248
	v_rcp_f32_e32 v249, v249
	v_rcp_f32_e32 v250, v250
	v_rcp_f32_e32 v251, v251
	v_lshlrev_b32_e32 v206, 16, v136
	v_and_b32_e32 v207, 0xffff0000, v136
	v_lshlrev_b32_e32 v208, 16, v137
	v_and_b32_e32 v209, 0xffff0000, v137
	v_lshlrev_b32_e32 v190, 16, v138
	v_and_b32_e32 v191, 0xffff0000, v138
	v_lshlrev_b32_e32 v192, 16, v139
	v_and_b32_e32 v193, 0xffff0000, v139
	v_pk_mul_f32 v[206:207], v[206:207], v[244:245]
	v_pk_mul_f32 v[208:209], v[208:209], v[246:247]
	v_pk_mul_f32 v[190:191], v[190:191], v[248:249]
	v_pk_mul_f32 v[192:193], v[192:193], v[250:251]
	v_pk_mul_f32 v[4:5], v[4:5], v[206:207]
	v_pk_mul_f32 v[6:7], v[6:7], v[208:209]
	v_pk_mul_f32 v[0:1], v[0:1], v[190:191]
	v_pk_mul_f32 v[2:3], v[2:3], v[192:193]
	s_branch .LBB0_1056
; #define GAS __attribute__((address_space(1)))
; __device__ __forceinline__ float bf_lo(unsigned u) { return __uint_as_float(u << 16); }
; __device__ __forceinline__ float bf_hi(unsigned u) { return __uint_as_float(u & 0xffff0000u); }
; __device__ __forceinline__ float frcp(float x) { return __builtin_amdgcn_rcpf(x); }
; __device__ __forceinline__ v4u pack8(const f32x4 a, const f32x4 b) { v4u w; w.x = cvt_pk_bf16(a[0], a[1]); w.y = cvt_pk_bf16(a[2], a[3]); w.z = cvt_pk_bf16(b[0], b[1]); w.w = cvt_pk_bf16(b[2], b[3]); return w; }
;     __device__ __forceinline__ void operator()(Acc& acc, const Unit& u, int wr, int wc, int fr, int fq, LAS unsigned char* lds) const {
;     ...
;                 for (int bj = 0; bj < 2; ++bj) { const size_t ro = (size_t)(row0 + ai * 128 + (2 * mh + mm) * 16) * 1024 + c0 + bj * 128; ga[mm][bj] = *(const GAS v4u*)(G0 + ro); gb[mm][bj] = fin ? ga[mm][bj] : *(const GAS v4u*)(G1 + ro); }
; #pragma unroll
;             for (int mm = 0; mm < 2; ++mm)
; #pragma unroll
;                 for (int bj = 0; bj < 2; ++bj) { const int m = 2 * mh + mm; const v4u x = ga[mm][bj], y = gb[mm][bj];
;                     f32x4 fa0 = {bf_lo(x.x), bf_hi(x.x), bf_lo(x.y), bf_hi(x.y)}, fa1 = {bf_lo(x.z), bf_hi(x.z), bf_lo(x.w), bf_hi(x.w)};
;                     if (!fin) { const f32x4 fb0 = {bf_lo(y.x), bf_hi(y.x), bf_lo(y.y), bf_hi(y.y)}, fb1 = {bf_lo(y.z), bf_hi(y.z), bf_lo(y.w), bf_hi(y.w)};
; #pragma unroll
;                         for (int j = 0; j < 4; ++j) { fa0[j] *= frcp(fb0[j]); fa1[j] *= frcp(fb1[j]); } }
;                     acc[ai][bj][m][0] *= fa0; acc[ai][bj][m][1] *= fa1;
;                     if (fin) *(GAS v4u*)(dst + (size_t)(row0 + ai * 128 + m * 16) * 1024 + c0 + bj * 128) = pack8(acc[ai][bj][m][0], acc[ai][bj][m][1]); }
.Lmg_fin:
	global_load_dwordx4 v[128:131], v182, s[52:53]
	global_load_dwordx4 v[136:139], v182, s[52:53] offset:256
	global_load_dwordx4 v[144:147], v183, s[52:53]
	global_load_dwordx4 v[152:155], v183, s[52:53] offset:256
	global_load_dwordx4 v[218:221], v184, s[52:53]
	global_load_dwordx4 v[226:229], v184, s[52:53] offset:256
	global_load_dwordx4 v[198:201], v185, s[52:53]
	s_waitcnt vmcnt(6)
	v_lshlrev_b32_e32 v206, 16, v128
	v_and_b32_e32 v207, 0xffff0000, v128
	v_lshlrev_b32_e32 v208, 16, v129
	v_and_b32_e32 v209, 0xffff0000, v129
	v_lshlrev_b32_e32 v190, 16, v130
	v_and_b32_e32 v191, 0xffff0000, v130
	v_lshlrev_b32_e32 v192, 16, v131
	v_and_b32_e32 v193, 0xffff0000, v131
	global_load_dwordx4 v[128:131], v185, s[52:53] offset:256
	v_pk_mul_f32 v[124:125], v[124:125], v[206:207]
	v_pk_mul_f32 v[126:127], v[126:127], v[208:209]
	v_pk_mul_f32 v[120:121], v[120:121], v[190:191]
	v_pk_mul_f32 v[122:123], v[122:123], v[192:193]
	v_cvt_pk_bf16_f32 v244, v124, v125
	v_cvt_pk_bf16_f32 v245, v126, v127
	v_cvt_pk_bf16_f32 v246, v120, v121
	v_cvt_pk_bf16_f32 v247, v122, v123
	s_nop 0
	global_store_dwordx4 v182, v[244:247], s[8:9]
	s_waitcnt vmcnt(7)
	v_lshlrev_b32_e32 v206, 16, v136
	v_and_b32_e32 v207, 0xffff0000, v136
	v_lshlrev_b32_e32 v208, 16, v137
	v_and_b32_e32 v209, 0xffff0000, v137
	v_lshlrev_b32_e32 v190, 16, v138
	v_and_b32_e32 v191, 0xffff0000, v138
	v_lshlrev_b32_e32 v192, 16, v139
	v_and_b32_e32 v193, 0xffff0000, v139
	global_load_dwordx4 v[136:139], v186, s[52:53]
	v_pk_mul_f32 v[92:93], v[92:93], v[206:207]
	v_pk_mul_f32 v[94:95], v[94:95], v[208:209]
	v_pk_mul_f32 v[88:89], v[88:89], v[190:191]
	v_pk_mul_f32 v[90:91], v[90:91], v[192:193]
	v_cvt_pk_bf16_f32 v248, v92, v93
	v_cvt_pk_bf16_f32 v249, v94, v95
	v_cvt_pk_bf16_f32 v250, v88, v89
	v_cvt_pk_bf16_f32 v251, v90, v91
	s_nop 0
	global_store_dwordx4 v182, v[248:251], s[8:9] offset:256
	s_waitcnt vmcnt(8)
	v_lshlrev_b32_e32 v206, 16, v144
	v_and_b32_e32 v207, 0xffff0000, v144
	v_lshlrev_b32_e32 v208, 16, v145
	v_and_b32_e32 v209, 0xffff0000, v145
	v_lshlrev_b32_e32 v190, 16, v146
	v_and_b32_e32 v191, 0xffff0000, v146
	v_lshlrev_b32_e32 v192, 16, v147
	v_and_b32_e32 v193, 0xffff0000, v147
	global_load_dwordx4 v[144:147], v186, s[52:53] offset:256
	v_pk_mul_f32 v[116:117], v[116:117], v[206:207]
	v_pk_mul_f32 v[118:119], v[118:119], v[208:209]
	v_pk_mul_f32 v[112:113], v[112:113], v[190:191]
	v_pk_mul_f32 v[114:115], v[114:115], v[192:193]
	v_cvt_pk_bf16_f32 v244, v116, v117
	v_cvt_pk_bf16_f32 v245, v118, v119
	v_cvt_pk_bf16_f32 v246, v112, v113
	v_cvt_pk_bf16_f32 v247, v114, v115
	s_nop 0
	global_store_dwordx4 v183, v[244:247], s[8:9]
	s_waitcnt vmcnt(9)
	v_lshlrev_b32_e32 v206, 16, v152
	v_and_b32_e32 v207, 0xffff0000, v152
	v_lshlrev_b32_e32 v208, 16, v153
	v_and_b32_e32 v209, 0xffff0000, v153
	v_lshlrev_b32_e32 v190, 16, v154
	v_and_b32_e32 v191, 0xffff0000, v154
	v_lshlrev_b32_e32 v192, 16, v155
	v_and_b32_e32 v193, 0xffff0000, v155
	global_load_dwordx4 v[152:155], v187, s[52:53]
	v_pk_mul_f32 v[84:85], v[84:85], v[206:207]
	v_pk_mul_f32 v[86:87], v[86:87], v[208:209]
	v_pk_mul_f32 v[80:81], v[80:81], v[190:191]
	v_pk_mul_f32 v[82:83], v[82:83], v[192:193]
	v_cvt_pk_bf16_f32 v248, v84, v85
	v_cvt_pk_bf16_f32 v249, v86, v87
	v_cvt_pk_bf16_f32 v250, v80, v81
	v_cvt_pk_bf16_f32 v251, v82, v83
	s_nop 0
	global_store_dwordx4 v183, v[248:251], s[8:9] offset:256
	s_waitcnt vmcnt(10)
	v_lshlrev_b32_e32 v206, 16, v218
	v_and_b32_e32 v207, 0xffff0000, v218
	v_lshlrev_b32_e32 v208, 16, v219
	v_and_b32_e32 v209, 0xffff0000, v219
	v_lshlrev_b32_e32 v190, 16, v220
	v_and_b32_e32 v191, 0xffff0000, v220
	v_lshlrev_b32_e32 v192, 16, v221
	v_and_b32_e32 v193, 0xffff0000, v221
	global_load_dwordx4 v[218:221], v187, s[52:53] offset:256
	v_pk_mul_f32 v[108:109], v[108:109], v[206:207]
	v_pk_mul_f32 v[110:111], v[110:111], v[208:209]
	v_pk_mul_f32 v[104:105], v[104:105], v[190:191]
	v_pk_mul_f32 v[106:107], v[106:107], v[192:193]
	v_cvt_pk_bf16_f32 v244, v108, v109
	v_cvt_pk_bf16_f32 v245, v110, v111
	v_cvt_pk_bf16_f32 v246, v104, v105
	v_cvt_pk_bf16_f32 v247, v106, v107
	s_nop 0
	global_store_dwordx4 v184, v[244:247], s[8:9]
	s_waitcnt vmcnt(11)
	v_lshlrev_b32_e32 v206, 16, v226
	v_and_b32_e32 v207, 0xffff0000, v226
	v_lshlrev_b32_e32 v208, 16, v227
	v_and_b32_e32 v209, 0xffff0000, v227
	v_lshlrev_b32_e32 v190, 16, v228
	v_and_b32_e32 v191, 0xffff0000, v228
	v_lshlrev_b32_e32 v192, 16, v229
	v_and_b32_e32 v193, 0xffff0000, v229
	global_load_dwordx4 v[226:229], v188, s[52:53]
	v_pk_mul_f32 v[76:77], v[76:77], v[206:207]
	v_pk_mul_f32 v[78:79], v[78:79], v[208:209]
	v_pk_mul_f32 v[72:73], v[72:73], v[190:191]
	v_pk_mul_f32 v[74:75], v[74:75], v[192:193]
	v_cvt_pk_bf16_f32 v248, v76, v77
	v_cvt_pk_bf16_f32 v249, v78, v79
	v_cvt_pk_bf16_f32 v250, v72, v73
	v_cvt_pk_bf16_f32 v251, v74, v75
	s_nop 0
	global_store_dwordx4 v184, v[248:251], s[8:9] offset:256
	s_waitcnt vmcnt(12)
	v_lshlrev_b32_e32 v206, 16, v198
	v_and_b32_e32 v207, 0xffff0000, v198
	v_lshlrev_b32_e32 v208, 16, v199
	v_and_b32_e32 v209, 0xffff0000, v199
	v_lshlrev_b32_e32 v190, 16, v200
	v_and_b32_e32 v191, 0xffff0000, v200
	v_lshlrev_b32_e32 v192, 16, v201
	v_and_b32_e32 v193, 0xffff0000, v201
	global_load_dwordx4 v[198:201], v188, s[52:53] offset:256
	v_pk_mul_f32 v[100:101], v[100:101], v[206:207]
	v_pk_mul_f32 v[102:103], v[102:103], v[208:209]
	v_pk_mul_f32 v[96:97], v[96:97], v[190:191]
	v_pk_mul_f32 v[98:99], v[98:99], v[192:193]
	v_cvt_pk_bf16_f32 v244, v100, v101
	v_cvt_pk_bf16_f32 v245, v102, v103
	v_cvt_pk_bf16_f32 v246, v96, v97
	v_cvt_pk_bf16_f32 v247, v98, v99
	s_nop 0
	global_store_dwordx4 v185, v[244:247], s[8:9]
	s_waitcnt vmcnt(13)
; #define GAS __attribute__((address_space(1)))
; __device__ __forceinline__ float bf_lo(unsigned u) { return __uint_as_float(u << 16); }
; __device__ __forceinline__ float bf_hi(unsigned u) { return __uint_as_float(u & 0xffff0000u); }
; __device__ __forceinline__ float frcp(float x) { return __builtin_amdgcn_rcpf(x); }
; __device__ __forceinline__ v4u pack8(const f32x4 a, const f32x4 b) { v4u w; w.x = cvt_pk_bf16(a[0], a[1]); w.y = cvt_pk_bf16(a[2], a[3]); w.z = cvt_pk_bf16(b[0], b[1]); w.w = cvt_pk_bf16(b[2], b[3]); return w; }
;     __device__ __forceinline__ void operator()(Acc& acc, const Unit& u, int wr, int wc, int fr, int fq, LAS unsigned char* lds) const {
;     ...
;                 for (int bj = 0; bj < 2; ++bj) { const size_t ro = (size_t)(row0 + ai * 128 + (2 * mh + mm) * 16) * 1024 + c0 + bj * 128; ga[mm][bj] = *(const GAS v4u*)(G0 + ro); gb[mm][bj] = fin ? ga[mm][bj] : *(const GAS v4u*)(G1 + ro); }
; #pragma unroll
;             for (int mm = 0; mm < 2; ++mm)
; #pragma unroll
;                 for (int bj = 0; bj < 2; ++bj) { const int m = 2 * mh + mm; const v4u x = ga[mm][bj], y = gb[mm][bj];
;                     f32x4 fa0 = {bf_lo(x.x), bf_hi(x.x), bf_lo(x.y), bf_hi(x.y)}, fa1 = {bf_lo(x.z), bf_hi(x.z), bf_lo(x.w), bf_hi(x.w)};
;                     if (!fin) { const f32x4 fb0 = {bf_lo(y.x), bf_hi(y.x), bf_lo(y.y), bf_hi(y.y)}, fb1 = {bf_lo(y.z), bf_hi(y.z), bf_lo(y.w), bf_hi(y.w)};
; #pragma unroll
;                         for (int j = 0; j < 4; ++j) { fa0[j] *= frcp(fb0[j]); fa1[j] *= frcp(fb1[j]); } }
;                     acc[ai][bj][m][0] *= fa0; acc[ai][bj][m][1] *= fa1;
;                     if (fin) *(GAS v4u*)(dst + (size_t)(row0 + ai * 128 + m * 16) * 1024 + c0 + bj * 128) = pack8(acc[ai][bj][m][0], acc[ai][bj][m][1]); }
	v_lshlrev_b32_e32 v206, 16, v128
	v_and_b32_e32 v207, 0xffff0000, v128
	v_lshlrev_b32_e32 v208, 16, v129
	v_and_b32_e32 v209, 0xffff0000, v129
	v_lshlrev_b32_e32 v190, 16, v130
	v_and_b32_e32 v191, 0xffff0000, v130
	v_lshlrev_b32_e32 v192, 16, v131
	v_and_b32_e32 v193, 0xffff0000, v131
	global_load_dwordx4 v[128:131], v189, s[52:53]
	v_pk_mul_f32 v[68:69], v[68:69], v[206:207]
	v_pk_mul_f32 v[70:71], v[70:71], v[208:209]
	v_pk_mul_f32 v[64:65], v[64:65], v[190:191]
	v_pk_mul_f32 v[66:67], v[66:67], v[192:193]
	v_cvt_pk_bf16_f32 v248, v68, v69
	v_cvt_pk_bf16_f32 v249, v70, v71
	v_cvt_pk_bf16_f32 v250, v64, v65
	v_cvt_pk_bf16_f32 v251, v66, v67
	s_nop 0
	global_store_dwordx4 v185, v[248:251], s[8:9] offset:256
	s_waitcnt vmcnt(13)
	v_lshlrev_b32_e32 v206, 16, v136
	v_and_b32_e32 v207, 0xffff0000, v136
	v_lshlrev_b32_e32 v208, 16, v137
	v_and_b32_e32 v209, 0xffff0000, v137
	v_lshlrev_b32_e32 v190, 16, v138
	v_and_b32_e32 v191, 0xffff0000, v138
	v_lshlrev_b32_e32 v192, 16, v139
	v_and_b32_e32 v193, 0xffff0000, v139
	global_load_dwordx4 v[136:139], v189, s[52:53] offset:256
	v_pk_mul_f32 v[60:61], v[60:61], v[206:207]
	v_pk_mul_f32 v[62:63], v[62:63], v[208:209]
	v_pk_mul_f32 v[56:57], v[56:57], v[190:191]
	v_pk_mul_f32 v[58:59], v[58:59], v[192:193]
	v_cvt_pk_bf16_f32 v244, v60, v61
	v_cvt_pk_bf16_f32 v245, v62, v63
	v_cvt_pk_bf16_f32 v246, v56, v57
	v_cvt_pk_bf16_f32 v247, v58, v59
	s_nop 0
	global_store_dwordx4 v186, v[244:247], s[8:9]
	s_waitcnt vmcnt(13)
	v_lshlrev_b32_e32 v206, 16, v144
	v_and_b32_e32 v207, 0xffff0000, v144
	v_lshlrev_b32_e32 v208, 16, v145
	v_and_b32_e32 v209, 0xffff0000, v145
	v_lshlrev_b32_e32 v190, 16, v146
	v_and_b32_e32 v191, 0xffff0000, v146
	v_lshlrev_b32_e32 v192, 16, v147
	v_and_b32_e32 v193, 0xffff0000, v147
	v_pk_mul_f32 v[28:29], v[28:29], v[206:207]
	v_pk_mul_f32 v[30:31], v[30:31], v[208:209]
	v_pk_mul_f32 v[24:25], v[24:25], v[190:191]
	v_pk_mul_f32 v[26:27], v[26:27], v[192:193]
	v_cvt_pk_bf16_f32 v248, v28, v29
	v_cvt_pk_bf16_f32 v249, v30, v31
	v_cvt_pk_bf16_f32 v250, v24, v25
	v_cvt_pk_bf16_f32 v251, v26, v27
	s_nop 0
	global_store_dwordx4 v186, v[248:251], s[8:9] offset:256
	s_waitcnt vmcnt(12)
	v_lshlrev_b32_e32 v206, 16, v152
	v_and_b32_e32 v207, 0xffff0000, v152
	v_lshlrev_b32_e32 v208, 16, v153
	v_and_b32_e32 v209, 0xffff0000, v153
	v_lshlrev_b32_e32 v190, 16, v154
	v_and_b32_e32 v191, 0xffff0000, v154
	v_lshlrev_b32_e32 v192, 16, v155
	v_and_b32_e32 v193, 0xffff0000, v155
	v_pk_mul_f32 v[52:53], v[52:53], v[206:207]
	v_pk_mul_f32 v[54:55], v[54:55], v[208:209]
	v_pk_mul_f32 v[48:49], v[48:49], v[190:191]
	v_pk_mul_f32 v[50:51], v[50:51], v[192:193]
	v_cvt_pk_bf16_f32 v244, v52, v53
	v_cvt_pk_bf16_f32 v245, v54, v55
	v_cvt_pk_bf16_f32 v246, v48, v49
	v_cvt_pk_bf16_f32 v247, v50, v51
	s_nop 0
	global_store_dwordx4 v187, v[244:247], s[8:9]
	s_waitcnt vmcnt(11)
	v_lshlrev_b32_e32 v206, 16, v218
	v_and_b32_e32 v207, 0xffff0000, v218
	v_lshlrev_b32_e32 v208, 16, v219
	v_and_b32_e32 v209, 0xffff0000, v219
	v_lshlrev_b32_e32 v190, 16, v220
	v_and_b32_e32 v191, 0xffff0000, v220
	v_lshlrev_b32_e32 v192, 16, v221
	v_and_b32_e32 v193, 0xffff0000, v221
	v_pk_mul_f32 v[20:21], v[20:21], v[206:207]
	v_pk_mul_f32 v[22:23], v[22:23], v[208:209]
	v_pk_mul_f32 v[16:17], v[16:17], v[190:191]
	v_pk_mul_f32 v[18:19], v[18:19], v[192:193]
	v_cvt_pk_bf16_f32 v248, v20, v21
	v_cvt_pk_bf16_f32 v249, v22, v23
	v_cvt_pk_bf16_f32 v250, v16, v17
	v_cvt_pk_bf16_f32 v251, v18, v19
	s_nop 0
	global_store_dwordx4 v187, v[248:251], s[8:9] offset:256
	s_waitcnt vmcnt(10)
	v_lshlrev_b32_e32 v206, 16, v226
	v_and_b32_e32 v207, 0xffff0000, v226
	v_lshlrev_b32_e32 v208, 16, v227
	v_and_b32_e32 v209, 0xffff0000, v227
	v_lshlrev_b32_e32 v190, 16, v228
	v_and_b32_e32 v191, 0xffff0000, v228
	v_lshlrev_b32_e32 v192, 16, v229
	v_and_b32_e32 v193, 0xffff0000, v229
	v_pk_mul_f32 v[44:45], v[44:45], v[206:207]
	v_pk_mul_f32 v[46:47], v[46:47], v[208:209]
	v_pk_mul_f32 v[40:41], v[40:41], v[190:191]
	v_pk_mul_f32 v[42:43], v[42:43], v[192:193]
	v_cvt_pk_bf16_f32 v244, v44, v45
	v_cvt_pk_bf16_f32 v245, v46, v47
	v_cvt_pk_bf16_f32 v246, v40, v41
	v_cvt_pk_bf16_f32 v247, v42, v43
	s_nop 0
	global_store_dwordx4 v188, v[244:247], s[8:9]
	s_waitcnt vmcnt(9)
	v_lshlrev_b32_e32 v206, 16, v198
	v_and_b32_e32 v207, 0xffff0000, v198
	v_lshlrev_b32_e32 v208, 16, v199
	v_and_b32_e32 v209, 0xffff0000, v199
	v_lshlrev_b32_e32 v190, 16, v200
	v_and_b32_e32 v191, 0xffff0000, v200
	v_lshlrev_b32_e32 v192, 16, v201
	v_and_b32_e32 v193, 0xffff0000, v201
	v_pk_mul_f32 v[12:13], v[12:13], v[206:207]
	v_pk_mul_f32 v[14:15], v[14:15], v[208:209]
	v_pk_mul_f32 v[8:9], v[8:9], v[190:191]
	v_pk_mul_f32 v[10:11], v[10:11], v[192:193]
	v_cvt_pk_bf16_f32 v248, v12, v13
	v_cvt_pk_bf16_f32 v249, v14, v15
	v_cvt_pk_bf16_f32 v250, v8, v9
	v_cvt_pk_bf16_f32 v251, v10, v11
	s_nop 0
	global_store_dwordx4 v188, v[248:251], s[8:9] offset:256
	s_waitcnt vmcnt(8)
	v_lshlrev_b32_e32 v206, 16, v128
	v_and_b32_e32 v207, 0xffff0000, v128
	v_lshlrev_b32_e32 v208, 16, v129
	v_and_b32_e32 v209, 0xffff0000, v129
	v_lshlrev_b32_e32 v190, 16, v130
	v_and_b32_e32 v191, 0xffff0000, v130
	v_lshlrev_b32_e32 v192, 16, v131
	v_and_b32_e32 v193, 0xffff0000, v131
	v_pk_mul_f32 v[36:37], v[36:37], v[206:207]
	v_pk_mul_f32 v[38:39], v[38:39], v[208:209]
	v_pk_mul_f32 v[32:33], v[32:33], v[190:191]
	v_pk_mul_f32 v[34:35], v[34:35], v[192:193]
	v_cvt_pk_bf16_f32 v244, v36, v37
	v_cvt_pk_bf16_f32 v245, v38, v39
	v_cvt_pk_bf16_f32 v246, v32, v33
	v_cvt_pk_bf16_f32 v247, v34, v35
	s_nop 0
	global_store_dwordx4 v189, v[244:247], s[8:9]
	s_waitcnt vmcnt(7)
	v_lshlrev_b32_e32 v206, 16, v136
	v_and_b32_e32 v207, 0xffff0000, v136
	v_lshlrev_b32_e32 v208, 16, v137
	v_and_b32_e32 v209, 0xffff0000, v137
	v_lshlrev_b32_e32 v190, 16, v138
	v_and_b32_e32 v191, 0xffff0000, v138
	v_lshlrev_b32_e32 v192, 16, v139
	v_and_b32_e32 v193, 0xffff0000, v139
	v_pk_mul_f32 v[4:5], v[4:5], v[206:207]
	v_pk_mul_f32 v[6:7], v[6:7], v[208:209]
	v_pk_mul_f32 v[0:1], v[0:1], v[190:191]
	v_pk_mul_f32 v[2:3], v[2:3], v[192:193]
	v_cvt_pk_bf16_f32 v248, v4, v5
	v_cvt_pk_bf16_f32 v249, v6, v7
	v_cvt_pk_bf16_f32 v250, v0, v1
	v_cvt_pk_bf16_f32 v251, v2, v3
	s_nop 0
	global_store_dwordx4 v189, v[248:251], s[8:9] offset:256

; __global__ void __launch_bounds__(512, 2) mega_fwd(Params p) {
	.amdhsa_kernel _Z8mega_fwd6Params
		.amdhsa_group_segment_fixed_size 0
		.amdhsa_private_segment_fixed_size 0
		.amdhsa_kernarg_size 416
		.amdhsa_user_sgpr_count 2
		.amdhsa_user_sgpr_dispatch_ptr 0
		.amdhsa_user_sgpr_queue_ptr 0
		.amdhsa_user_sgpr_kernarg_segment_ptr 1
		.amdhsa_user_sgpr_dispatch_id 0
		.amdhsa_user_sgpr_kernarg_preload_length 0
		.amdhsa_user_sgpr_kernarg_preload_offset 0
		.amdhsa_user_sgpr_private_segment_size 0
		.amdhsa_uses_dynamic_stack 0
		.amdhsa_enable_private_segment 0
		.amdhsa_system_sgpr_workgroup_id_x 1
		.amdhsa_system_sgpr_workgroup_id_y 0
		.amdhsa_system_sgpr_workgroup_id_z 0
		.amdhsa_system_sgpr_workgroup_info 0
		.amdhsa_system_vgpr_workitem_id 0
		.amdhsa_next_free_vgpr 252
		.amdhsa_next_free_sgpr 98
		.amdhsa_accum_offset 252
		.amdhsa_reserve_vcc 1
		.amdhsa_float_round_mode_32 0
		.amdhsa_float_round_mode_16_64 0
		.amdhsa_float_denorm_mode_32 3
		.amdhsa_float_denorm_mode_16_64 3
		.amdhsa_dx10_clamp 1
		.amdhsa_ieee_mode 1
		.amdhsa_fp16_overflow 0
		.amdhsa_tg_split 0
		.amdhsa_exception_fp_ieee_invalid_op 0
		.amdhsa_exception_fp_denorm_src 0
		.amdhsa_exception_fp_ieee_div_zero 0
		.amdhsa_exception_fp_ieee_overflow 0
		.amdhsa_exception_fp_ieee_underflow 0
		.amdhsa_exception_fp_ieee_inexact 0
		.amdhsa_exception_int_div_zero 0
	.end_amdhsa_kernel

; __global__ void __launch_bounds__(512, 2) mega_fwd(Params p) {
amdhsa.kernels:
  - .agpr_count:     0
    .args:
      - .offset:         0
        .size:           160
        .value_kind:     by_value
      - .offset:         160
        .size:           4
        .value_kind:     hidden_block_count_x
      - .offset:         164
        .size:           4
        .value_kind:     hidden_block_count_y
      - .offset:         168
        .size:           4
        .value_kind:     hidden_block_count_z
      - .offset:         172
        .size:           2
        .value_kind:     hidden_group_size_x
      - .offset:         174
        .size:           2
        .value_kind:     hidden_group_size_y
      - .offset:         176
        .size:           2
        .value_kind:     hidden_group_size_z
      - .offset:         178
        .size:           2
        .value_kind:     hidden_remainder_x
      - .offset:         180
        .size:           2
        .value_kind:     hidden_remainder_y
      - .offset:         182
        .size:           2
        .value_kind:     hidden_remainder_z
      - .offset:         200
        .size:           8
        .value_kind:     hidden_global_offset_x
      - .offset:         208
        .size:           8
        .value_kind:     hidden_global_offset_y
      - .offset:         216
        .size:           8
        .value_kind:     hidden_global_offset_z
      - .offset:         224
        .size:           2
        .value_kind:     hidden_grid_dims
      - .offset:         280
        .size:           4
        .value_kind:     hidden_dynamic_lds_size
    .group_segment_fixed_size: 0
    .kernarg_segment_align: 8
    .kernarg_segment_size: 416
    .language:       OpenCL C
    .language_version:
      - 2
      - 0
    .max_flat_workgroup_size: 512
    .name:           _Z8mega_fwd6Params
    .private_segment_fixed_size: 0
    .sgpr_count:     104
    .sgpr_spill_count: 252
    .symbol:         _Z8mega_fwd6Params.kd
    .uniform_work_group_size: 1
    .uses_dynamic_stack: false
    .vgpr_count:     252
    .vgpr_spill_count: 0
    .wavefront_size: 64
